# k5 plus double-buffered K-fragment LDS reads with counted lgkmcnt in the QK blocks of mixer B score waves and mixer A
# speedup vs baseline: 1.0077x; 1.0076x over previous
; __device__ __forceinline__ void qkt(f32x16& p0, f32x16& p1, const char* Ks, const bf16x8* qr, int r32, int hi) {
;     p0 = f32x16{}; p1 = f32x16{};
; #pragma unroll
;     for (int d0 = 0; d0 < 8; ++d0) { const int cb = (d0 * 16 + hi * 8) * 2;
;         const bf16x8 b0 = *reinterpret_cast<const bf16x8*>(Ks + KSWZ(r32, cb));
;         const bf16x8 b1 = *reinterpret_cast<const bf16x8*>(Ks + KSWZ(32 + r32, cb));
;         p0 = __builtin_amdgcn_mfma_f32_32x32x16_bf16(b0, qr[d0], p0, 0, 0, 0);
;         p1 = __builtin_amdgcn_mfma_f32_32x32x16_bf16(b1, qr[d0], p1, 0, 0, 0); }
; template <int MODE>
; __device__ __forceinline__ void flash_core(const bf16_t* __restrict__ Qg, const bf16_t* __restrict__ Kg, const bf16_t* __restrict__ Vg,
;                                            int jlo, int jhi, int wlo, int whi, int qpos0, float slope2, char* lds, f32x16 (&o)[4], float& l_out) {
;     ...
;         if (j >= wlo && j <= whi) {
;             f32x16 p0, p1;
;             qkt(p0, p1, Kb, qr, r32, hi);
;             const int kb = 64 * j + 4 * hi;
;             if (MODE == 0) {
;                 if (64 * j + 63 - qpos0 <= -128) { const float c = tbl[0];
; #pragma unroll
;                     for (int r = 0; r < 16; ++r) { p0[r] += c; p1[r] += c; }
;                 } else {
; #pragma unroll
;                     for (int r = 0; r < 16; ++r) { const int rel = kb + (r & 3) + 8 * (r >> 2) - qp;
;                         const int i0 = min(max(rel, -128), 128) + 128, i1 = min(max(rel + 32, -128), 128) + 128;
;                         p0[r] += tbl[i0]; p1[r] += tbl[i1]; }
.LBB0_417:
	s_cmp_lt_u32 s71, s66
	s_cselect_b64 s[2:3], -1, 0
	s_cmp_gt_i32 s71, s16
	s_cselect_b64 s[40:41], -1, 0
	s_or_b64 s[2:3], s[2:3], s[40:41]
	s_and_b64 vcc, exec, s[2:3]
	s_cbranch_vccnz .LBB0_412
	s_add_i32 s2, s30, 0
	v_add3_u32 v0, s2, v163, v159
	ds_read_b128 v[2:5], v0
	ds_read_b128 v[6:9], v0 offset:8192
	v_add3_u32 v0, s2, v191, v159
	s_mov_b64 s[40:41], -1
	ds_read_b128 v[210:213], v0
	ds_read_b128 v[214:217], v0 offset:8192
	v_add3_u32 v0, s2, v192, v159
	s_waitcnt lgkmcnt(2)
	v_mfma_f32_32x32x16_bf16 v[80:95], v[2:5], v[112:115], 0
	v_mfma_f32_32x32x16_bf16 v[96:111], v[6:9], v[112:115], 0
	ds_read_b128 v[2:5], v0
	ds_read_b128 v[6:9], v0 offset:8192
	v_add3_u32 v0, s2, v193, v159
	s_waitcnt lgkmcnt(2)
	v_mfma_f32_32x32x16_bf16 v[80:95], v[210:213], v[116:119], v[80:95]
	v_mfma_f32_32x32x16_bf16 v[96:111], v[214:217], v[116:119], v[96:111]
	ds_read_b128 v[210:213], v0
	ds_read_b128 v[214:217], v0 offset:8192
	v_add3_u32 v0, s2, v194, v159
	s_waitcnt lgkmcnt(2)
	v_mfma_f32_32x32x16_bf16 v[80:95], v[2:5], v[120:123], v[80:95]
	v_mfma_f32_32x32x16_bf16 v[96:111], v[6:9], v[120:123], v[96:111]
	ds_read_b128 v[2:5], v0
	ds_read_b128 v[6:9], v0 offset:8192
	v_add3_u32 v0, s2, v195, v159
	s_waitcnt lgkmcnt(2)
	v_mfma_f32_32x32x16_bf16 v[80:95], v[210:213], v[124:127], v[80:95]
	v_mfma_f32_32x32x16_bf16 v[96:111], v[214:217], v[124:127], v[96:111]
	ds_read_b128 v[210:213], v0
	ds_read_b128 v[214:217], v0 offset:8192
	v_add3_u32 v0, s2, v196, v159
	s_waitcnt lgkmcnt(2)
	v_mfma_f32_32x32x16_bf16 v[80:95], v[2:5], v[128:131], v[80:95]
	v_mfma_f32_32x32x16_bf16 v[96:111], v[6:9], v[128:131], v[96:111]
	ds_read_b128 v[2:5], v0
	ds_read_b128 v[6:9], v0 offset:8192
	v_add3_u32 v0, s2, v197, v159
	s_add_i32 s2, s67, s70
	s_cmpk_lt_i32 s2, 0xff81
	s_waitcnt lgkmcnt(2)
	v_mfma_f32_32x32x16_bf16 v[80:95], v[210:213], v[132:135], v[80:95]
	v_mfma_f32_32x32x16_bf16 v[96:111], v[214:217], v[132:135], v[96:111]
	s_waitcnt lgkmcnt(0)
	v_mfma_f32_32x32x16_bf16 v[80:95], v[2:5], v[136:139], v[80:95]
	ds_read_b128 v[2:5], v0
	ds_read_b128 v[206:209], v0 offset:8192
	v_mfma_f32_32x32x16_bf16 v[96:111], v[6:9], v[136:139], v[96:111]
	s_waitcnt lgkmcnt(0)
	v_mfma_f32_32x32x16_bf16 v[80:95], v[2:5], v[140:143], v[80:95]
	v_mfma_f32_32x32x16_bf16 v[96:111], v[206:209], v[140:143], v[96:111]
	s_cbranch_scc1 .LBB0_420
	v_add_u32_e32 v0, s67, v201
	v_add_u32_e32 v2, 0xfffffe00, v0
	v_add_u32_e32 v4, 0xfffffe01, v0
	v_add_u32_e32 v8, 0xfffffe03, v0
	v_med3_i32 v3, v2, s44, v155
	v_med3_i32 v2, v2, s45, v157
	v_med3_i32 v5, v4, s44, v155
	v_med3_i32 v4, v4, s45, v157
	v_add_u32_e32 v6, 0xfffffe02, v0
	v_med3_i32 v9, v8, s44, v155
	v_med3_i32 v8, v8, s45, v157
	v_lshl_add_u32 v3, v3, 2, s0
	v_lshl_add_u32 v2, v2, 2, s0
	v_lshl_add_u32 v5, v5, 2, s0
	v_lshl_add_u32 v4, v4, 2, s0
	v_med3_i32 v7, v6, s44, v155
	v_med3_i32 v6, v6, s45, v157
	v_lshl_add_u32 v8, v8, 2, s0
	v_lshl_add_u32 v7, v7, 2, s0
	v_lshl_add_u32 v6, v6, 2, s0
	v_lshl_add_u32 v9, v9, 2, s0
	ds_read_b32 v172, v3 offset:512
	ds_read_b32 v2, v2 offset:640
	ds_read_b32 v173, v5 offset:512
	ds_read_b32 v3, v4 offset:640
	ds_read_b32 v174, v7 offset:512
	ds_read_b32 v4, v6 offset:640
	ds_read_b32 v175, v9 offset:512
	ds_read_b32 v5, v8 offset:640
	v_add_u32_e32 v8, 0xfffffe09, v0
	v_med3_i32 v9, v8, s44, v155
	v_med3_i32 v8, v8, s45, v157
	v_lshl_add_u32 v10, v8, 2, s0
	v_add_u32_e32 v8, 0xfffffe0a, v0
	v_med3_i32 v11, v8, s44, v155
	v_med3_i32 v8, v8, s45, v157
	v_add_u32_e32 v6, 0xfffffe08, v0
	v_lshl_add_u32 v12, v8, 2, s0
	v_add_u32_e32 v8, 0xfffffe0b, v0
	v_med3_i32 v7, v6, s44, v155
	v_med3_i32 v13, v8, s44, v155
	v_med3_i32 v8, v8, s45, v157
	v_med3_i32 v6, v6, s45, v157
	v_lshl_add_u32 v7, v7, 2, s0
	v_lshl_add_u32 v9, v9, 2, s0
	v_lshl_add_u32 v14, v13, 2, s0
	v_lshl_add_u32 v13, v8, 2, s0
	v_lshl_add_u32 v6, v6, 2, s0
	v_lshl_add_u32 v11, v11, 2, s0
	ds_read_b32 v176, v7 offset:512
	ds_read_b32 v8, v6 offset:640
	ds_read_b32 v177, v9 offset:512
	ds_read_b32 v9, v10 offset:640
	ds_read_b32 v178, v11 offset:512
	ds_read_b32 v12, v12 offset:640
	ds_read_b32 v13, v13 offset:640
	ds_read_b32 v179, v14 offset:512
	s_waitcnt lgkmcnt(0)
	v_pk_add_f32 v[10:11], v[96:97], v[2:3]
	v_pk_add_f32 v[6:7], v[98:99], v[4:5]
	v_pk_add_f32 v[4:5], v[100:101], v[8:9]
	v_pk_add_f32 v[2:3], v[102:103], v[12:13]
	v_add_u32_e32 v8, 0xfffffe10, v0
	v_add_u32_e32 v12, 0xfffffe11, v0
	v_add_u32_e32 v180, 0xfffffe13, v0
	v_med3_i32 v9, v8, s44, v155
	v_med3_i32 v8, v8, s45, v157
	v_med3_i32 v13, v12, s44, v155
	v_med3_i32 v12, v12, s45, v157
	v_add_u32_e32 v14, 0xfffffe12, v0
	v_med3_i32 v181, v180, s44, v155
	v_med3_i32 v180, v180, s45, v157
	v_lshl_add_u32 v9, v9, 2, s0
	v_lshl_add_u32 v8, v8, 2, s0
	v_lshl_add_u32 v13, v13, 2, s0
	v_lshl_add_u32 v12, v12, 2, s0
	v_med3_i32 v15, v14, s44, v155
	v_med3_i32 v14, v14, s45, v157
	v_lshl_add_u32 v183, v181, 2, s0
	v_lshl_add_u32 v184, v180, 2, s0
	v_lshl_add_u32 v15, v15, 2, s0
	v_lshl_add_u32 v14, v14, 2, s0
	ds_read_b32 v180, v9 offset:512
	ds_read_b32 v8, v8 offset:640
	ds_read_b32 v181, v13 offset:512
	ds_read_b32 v9, v12 offset:640
	ds_read_b32 v182, v15 offset:512
	ds_read_b32 v12, v14 offset:640
	ds_read_b32 v183, v183 offset:512
	ds_read_b32 v13, v184 offset:640
	v_add_u32_e32 v184, 0xfffffe19, v0
	v_med3_i32 v185, v184, s44, v155
	v_med3_i32 v184, v184, s45, v157
	v_lshl_add_u32 v186, v184, 2, s0
	v_add_u32_e32 v184, 0xfffffe1a, v0
	v_add_u32_e32 v14, 0xfffffe18, v0
	v_med3_i32 v187, v184, s44, v155
	v_med3_i32 v184, v184, s45, v157
	v_add_u32_e32 v0, 0xfffffe1b, v0
	v_med3_i32 v15, v14, s44, v155
	v_lshl_add_u32 v206, v184, 2, s0
	v_med3_i32 v184, v0, s44, v155
	v_med3_i32 v0, v0, s45, v157
	v_med3_i32 v14, v14, s45, v157
	v_lshl_add_u32 v15, v15, 2, s0
	v_lshl_add_u32 v185, v185, 2, s0
	v_lshl_add_u32 v187, v187, 2, s0
	v_lshl_add_u32 v0, v0, 2, s0
	v_lshl_add_u32 v14, v14, 2, s0
	v_lshl_add_u32 v207, v184, 2, s0
	ds_read_b32 v184, v15 offset:512
	ds_read_b32 v204, v14 offset:640
	ds_read_b32 v185, v185 offset:512
	ds_read_b32 v205, v186 offset:640
	ds_read_b32 v186, v187 offset:512
	ds_read_b32 v206, v206 offset:640
	ds_read_b32 v187, v207 offset:512
	ds_read_b32 v0, v0 offset:640
	s_waitcnt lgkmcnt(0)
	v_pk_add_f32 v[8:9], v[104:105], v[8:9]
	v_pk_add_f32 v[14:15], v[106:107], v[12:13]
	v_pk_add_f32 v[12:13], v[108:109], v[204:205]
	v_add_f32_e32 v204, v110, v206
	s_mov_b64 s[40:41], 0
